# phase 1 compress-bias loop: 64 k-values per iteration
# baseline (speedup 1.0000x reference)
.LBB0_277:
	s_mov_b64 s[8:9], 0x1000
	global_load_dwordx4 v[84:87], v[0:1], off
	global_load_dwordx4 v[88:91], v[0:1], off offset:16
	global_load_dwordx4 v[92:95], v[0:1], off offset:32
	global_load_dwordx4 v[96:99], v[0:1], off offset:48
	global_load_dwordx4 v[100:103], v[0:1], off offset:64
	global_load_dwordx4 v[104:107], v[0:1], off offset:80
	global_load_dwordx4 v[108:111], v[0:1], off offset:96
	global_load_dwordx4 v[112:115], v[0:1], off offset:112
	global_load_dwordx4 v[116:119], v[0:1], off offset:128
	global_load_dwordx4 v[120:123], v[0:1], off offset:144
	global_load_dwordx4 v[124:127], v[0:1], off offset:160
	global_load_dwordx4 v[128:131], v[0:1], off offset:176
	global_load_dwordx4 v[132:135], v[0:1], off offset:192
	global_load_dwordx4 v[136:139], v[0:1], off offset:208
	global_load_dwordx4 v[140:143], v[0:1], off offset:224
	global_load_dwordx4 v[144:147], v[0:1], off offset:240
	global_load_dword v22, v[2:3], off
	global_load_dword v23, v[2:3], off offset:1024
	global_load_dword v24, v[2:3], off offset:2048
	global_load_dword v25, v[2:3], off offset:3072
	v_lshl_add_u64 v[2:3], v[2:3], 0, s[8:9]
	global_load_dword v26, v[2:3], off
	global_load_dword v27, v[2:3], off offset:1024
	global_load_dword v28, v[2:3], off offset:2048
	global_load_dword v29, v[2:3], off offset:3072
	v_lshl_add_u64 v[2:3], v[2:3], 0, s[8:9]
	global_load_dword v30, v[2:3], off
	global_load_dword v31, v[2:3], off offset:1024
	global_load_dword v32, v[2:3], off offset:2048
	global_load_dword v33, v[2:3], off offset:3072
	v_lshl_add_u64 v[2:3], v[2:3], 0, s[8:9]
	global_load_dword v34, v[2:3], off
	global_load_dword v35, v[2:3], off offset:1024
	global_load_dword v36, v[2:3], off offset:2048
	global_load_dword v37, v[2:3], off offset:3072
	v_lshl_add_u64 v[2:3], v[2:3], 0, s[8:9]
	global_load_dword v38, v[2:3], off
	global_load_dword v39, v[2:3], off offset:1024
	global_load_dword v40, v[2:3], off offset:2048
	global_load_dword v41, v[2:3], off offset:3072
	v_lshl_add_u64 v[2:3], v[2:3], 0, s[8:9]
	global_load_dword v42, v[2:3], off
	global_load_dword v43, v[2:3], off offset:1024
	global_load_dword v44, v[2:3], off offset:2048
	global_load_dword v45, v[2:3], off offset:3072
	v_lshl_add_u64 v[2:3], v[2:3], 0, s[8:9]
	global_load_dword v46, v[2:3], off
	global_load_dword v47, v[2:3], off offset:1024
	global_load_dword v48, v[2:3], off offset:2048
	global_load_dword v49, v[2:3], off offset:3072
	v_lshl_add_u64 v[2:3], v[2:3], 0, s[8:9]
	global_load_dword v50, v[2:3], off
	global_load_dword v51, v[2:3], off offset:1024
	global_load_dword v52, v[2:3], off offset:2048
	global_load_dword v53, v[2:3], off offset:3072
	v_lshl_add_u64 v[2:3], v[2:3], 0, s[8:9]
	global_load_dword v54, v[2:3], off
	global_load_dword v55, v[2:3], off offset:1024
	global_load_dword v56, v[2:3], off offset:2048
	global_load_dword v57, v[2:3], off offset:3072
	v_lshl_add_u64 v[2:3], v[2:3], 0, s[8:9]
	global_load_dword v58, v[2:3], off
	global_load_dword v59, v[2:3], off offset:1024
	global_load_dword v60, v[2:3], off offset:2048
	global_load_dword v61, v[2:3], off offset:3072
	v_lshl_add_u64 v[2:3], v[2:3], 0, s[8:9]
	global_load_dword v62, v[2:3], off
	global_load_dword v63, v[2:3], off offset:1024
	global_load_dword v64, v[2:3], off offset:2048
	global_load_dword v65, v[2:3], off offset:3072
	v_lshl_add_u64 v[2:3], v[2:3], 0, s[8:9]
	global_load_dword v66, v[2:3], off
	global_load_dword v67, v[2:3], off offset:1024
	global_load_dword v68, v[2:3], off offset:2048
	global_load_dword v69, v[2:3], off offset:3072
	v_lshl_add_u64 v[2:3], v[2:3], 0, s[8:9]
	global_load_dword v70, v[2:3], off
	global_load_dword v71, v[2:3], off offset:1024
	global_load_dword v72, v[2:3], off offset:2048
	global_load_dword v73, v[2:3], off offset:3072
	v_lshl_add_u64 v[2:3], v[2:3], 0, s[8:9]
	global_load_dword v74, v[2:3], off
	global_load_dword v75, v[2:3], off offset:1024
	global_load_dword v76, v[2:3], off offset:2048
	global_load_dword v77, v[2:3], off offset:3072
	v_lshl_add_u64 v[2:3], v[2:3], 0, s[8:9]
	global_load_dword v148, v[2:3], off
	global_load_dword v149, v[2:3], off offset:1024
	global_load_dword v150, v[2:3], off offset:2048
	global_load_dword v151, v[2:3], off offset:3072
	v_lshl_add_u64 v[2:3], v[2:3], 0, s[8:9]
	global_load_dword v152, v[2:3], off
	global_load_dword v153, v[2:3], off offset:1024
	global_load_dword v154, v[2:3], off offset:2048
	global_load_dword v155, v[2:3], off offset:3072
	v_lshl_add_u64 v[2:3], v[2:3], 0, s[8:9]
	v_add_u32_e32 v7, 64, v7
	v_cmp_ge_i32_e32 vcc, v7, v6
	v_lshl_add_u64 v[0:1], v[0:1], 0, 64
	v_lshl_add_u64 v[0:1], v[0:1], 0, 64
	v_lshl_add_u64 v[0:1], v[0:1], 0, 64
	v_lshl_add_u64 v[0:1], v[0:1], 0, 64
	s_or_b64 s[6:7], vcc, s[6:7]
	s_waitcnt vmcnt(0)
	v_fmac_f32_e32 v8, v84, v22
	v_fmac_f32_e32 v8, v85, v23
	v_fmac_f32_e32 v8, v86, v24
	v_fmac_f32_e32 v8, v87, v25
	v_fmac_f32_e32 v8, v88, v26
	v_fmac_f32_e32 v8, v89, v27
	v_fmac_f32_e32 v8, v90, v28
	v_fmac_f32_e32 v8, v91, v29
	v_fmac_f32_e32 v8, v92, v30
	v_fmac_f32_e32 v8, v93, v31
	v_fmac_f32_e32 v8, v94, v32
	v_fmac_f32_e32 v8, v95, v33
	v_fmac_f32_e32 v8, v96, v34
	v_fmac_f32_e32 v8, v97, v35
	v_fmac_f32_e32 v8, v98, v36
	v_fmac_f32_e32 v8, v99, v37
	v_fmac_f32_e32 v8, v100, v38
	v_fmac_f32_e32 v8, v101, v39
	v_fmac_f32_e32 v8, v102, v40
	v_fmac_f32_e32 v8, v103, v41
	v_fmac_f32_e32 v8, v104, v42
	v_fmac_f32_e32 v8, v105, v43
	v_fmac_f32_e32 v8, v106, v44
	v_fmac_f32_e32 v8, v107, v45
	v_fmac_f32_e32 v8, v108, v46
	v_fmac_f32_e32 v8, v109, v47
	v_fmac_f32_e32 v8, v110, v48
	v_fmac_f32_e32 v8, v111, v49
	v_fmac_f32_e32 v8, v112, v50
	v_fmac_f32_e32 v8, v113, v51
	v_fmac_f32_e32 v8, v114, v52
	v_fmac_f32_e32 v8, v115, v53
	v_fmac_f32_e32 v8, v116, v54
	v_fmac_f32_e32 v8, v117, v55
	v_fmac_f32_e32 v8, v118, v56
	v_fmac_f32_e32 v8, v119, v57
	v_fmac_f32_e32 v8, v120, v58
	v_fmac_f32_e32 v8, v121, v59
	v_fmac_f32_e32 v8, v122, v60
	v_fmac_f32_e32 v8, v123, v61
	v_fmac_f32_e32 v8, v124, v62
	v_fmac_f32_e32 v8, v125, v63
	v_fmac_f32_e32 v8, v126, v64
	v_fmac_f32_e32 v8, v127, v65
	v_fmac_f32_e32 v8, v128, v66
	v_fmac_f32_e32 v8, v129, v67
	v_fmac_f32_e32 v8, v130, v68
	v_fmac_f32_e32 v8, v131, v69
	v_fmac_f32_e32 v8, v132, v70
	v_fmac_f32_e32 v8, v133, v71
	v_fmac_f32_e32 v8, v134, v72
	v_fmac_f32_e32 v8, v135, v73
	v_fmac_f32_e32 v8, v136, v74
	v_fmac_f32_e32 v8, v137, v75
	v_fmac_f32_e32 v8, v138, v76
	v_fmac_f32_e32 v8, v139, v77
	v_fmac_f32_e32 v8, v140, v148
	v_fmac_f32_e32 v8, v141, v149
	v_fmac_f32_e32 v8, v142, v150
	v_fmac_f32_e32 v8, v143, v151
	v_fmac_f32_e32 v8, v144, v152
	v_fmac_f32_e32 v8, v145, v153
	v_fmac_f32_e32 v8, v146, v154
	v_fmac_f32_e32 v8, v147, v155
	s_andn2_b64 exec, exec, s[6:7]
	s_cbranch_execnz .LBB0_277
	s_or_b64 exec, exec, s[6:7]
	v_lshlrev_b32_e32 v0, 2, v20
	v_cmp_gt_i32_e32 vcc, 32, v20
	ds_write_b32 v0, v8
	s_waitcnt lgkmcnt(0)
	s_barrier
	s_and_saveexec_b64 s[6:7], vcc
	s_cbranch_execz .LBB0_280
	ds_read2_b32 v[2:3], v0 offset1:32
	v_readlane_b32 s5, v251, 46
	s_waitcnt lgkmcnt(0)
	v_add_f32_e32 v1, v3, v2
	ds_read2_b32 v[2:3], v0 offset0:64 offset1:96
	s_waitcnt lgkmcnt(0)
	v_add_f32_e32 v1, v1, v2
	v_add_f32_e32 v1, v1, v3
	ds_read2_b32 v[2:3], v0 offset0:128 offset1:160
	s_waitcnt lgkmcnt(0)
	v_add_f32_e32 v1, v1, v2
	v_add_f32_e32 v2, v1, v3
	ds_read2_b32 v[0:1], v0 offset0:192 offset1:224
	s_waitcnt lgkmcnt(0)
	v_add_f32_e32 v0, v2, v0
	v_add_f32_e32 v2, v0, v1
	v_add_u32_e32 v0, s5, v20
	v_ashrrev_i32_e32 v1, 31, v0
	v_lshl_add_u64 v[0:1], v[0:1], 2, s[0:1]
	v_add_co_u32_e32 v0, vcc, 0xe280000, v0
	s_nop 1
	v_addc_co_u32_e32 v1, vcc, 0, v1, vcc
	global_store_dword v[0:1], v2, off
